# grid barrier: three polls of the TOP counter kept in flight (detection delay about one third of a round trip)
# speedup vs baseline: 1.0017x; 1.0017x over previous
; __device__ __forceinline__ unsigned xb_ld(unsigned* p)              { return __hip_atomic_load(p, __ATOMIC_RELAXED, __HIP_MEMORY_SCOPE_AGENT); }
; __device__ __forceinline__ unsigned xb_add(unsigned* p, unsigned v) { return __hip_atomic_fetch_add(p, v, __ATOMIC_RELAXED, __HIP_MEMORY_SCOPE_AGENT); }
; #define XB_SPIN(cond, bar) do { unsigned _sp = 0; while (cond) { __builtin_amdgcn_s_sleep(1); \
;     if ((++_sp & 255u) == 0u) { if (xb_ld(&(bar)[XB_TMO])) break; if (_sp > XB_SPIN_CAP) { atomicAdd(&(bar)[XB_TMO], 1u); break; } } } } while (0)
; __device__ __forceinline__ void xcd_barrier(const XcdBarrier& b) {
;     ...
;         const unsigned old = xb_add(&bar[XB_XSUB(b.x)], 1u);
;         const unsigned gen = old / nloc;
;         if (old + 1u == (gen + 1u) * nloc) {
;             __builtin_amdgcn_fence(__ATOMIC_RELEASE, "agent");
;             asm volatile("s_waitcnt vmcnt(0)" ::: "memory");
;             const unsigned og = xb_add(&bar[XB_TOP], 1u);
;             const unsigned tg = og / nx;
;             if (og + 1u == (tg + 1u) * nx) xb_add(&bar[XB_TOPGEN], 1u);
;             else XB_SPIN(xb_ld(&bar[XB_TOPGEN]) == tg, bar);
;             __builtin_amdgcn_fence(__ATOMIC_ACQUIRE, "agent");
;             xb_add(&bar[XB_XGEN(b.x)], 1u);
;             asm volatile("s_waitcnt vmcnt(0)" ::: "memory");
;         } else {
;             XB_SPIN(xb_ld(&bar[XB_XGEN(b.x)]) == gen, bar);
;             __builtin_amdgcn_fence(__ATOMIC_ACQUIRE, "agent");
;             asm volatile("s_waitcnt vmcnt(0)" ::: "memory");
.Lxb_poll:
	s_mov_b32 s6, 0
	global_load_dword v1, v96, s[2:3] sc1
	s_sleep 8
	global_load_dword v2, v96, s[2:3] sc1
	s_sleep 8
	global_load_dword v3, v96, s[2:3] sc1
.Lxb_spin:
	s_waitcnt vmcnt(2)
	v_cmp_ge_u32_e32 vcc, v1, v4
	s_cbranch_vccnz .Lxb_done
	global_load_dword v1, v96, s[2:3] sc1
	s_waitcnt vmcnt(2)
	v_cmp_ge_u32_e32 vcc, v2, v4
	s_cbranch_vccnz .Lxb_done
	global_load_dword v2, v96, s[2:3] sc1
	s_waitcnt vmcnt(2)
	v_cmp_ge_u32_e32 vcc, v3, v4
	s_cbranch_vccnz .Lxb_done
	global_load_dword v3, v96, s[2:3] sc1
	s_add_i32 s6, s6, 1
	s_cmp_lt_u32 s6, 0x20000
	s_cbranch_scc1 .Lxb_spin
